# plus DA stash (map-0 partial O) re-laid out lane-contiguous: each stash load/store instruction now covers 1 KiB contiguous instead of 64 lines
# speedup vs baseline: 1.0199x; 1.0046x over previous
; __device__ __forceinline__ float hsum(float v) { auto rr = __builtin_amdgcn_permlane32_swap(__float_as_uint(v), __float_as_uint(v), false, false); return __uint_as_float(rr[0]) + __uint_as_float(rr[1]); }
; __device__ __forceinline__ void da_unit(LAS unsigned char* lds, const AttnP& P, int seqbase, int S, int h, int qb, float lam) {
;     ...
;         int tid3 = threadIdx.x; asm volatile("" : "+v"(tid3));
;         f32x4* stash = (f32x4*)(P.stash + (size_t)blockIdx.x * 32768 + tid3 * 64);
;         if (map == 0) {
;             const float inv = 1.0f / hsum(l);
; #pragma unroll
;             for (int db = 0; db < 4; ++db)
; #pragma unroll
;                 for (int g = 0; g < 4; ++g) stash[db * 4 + g] = (f32x4){o[db][4 * g], o[db][4 * g + 1], o[db][4 * g + 2], o[db][4 * g + 3]} * inv;
;         } else {
;             const float inv = lam / hsum(l);
; #pragma unroll
;             for (int db = 0; db < 4; ++db)
; #pragma unroll
;                 for (int g = 0; g < 4; ++g) {
;                     const f32x4 st = stash[db * 4 + g];
; #pragma unroll
;                     for (int e = 0; e < 4; ++e) { const float a = st[e] - o[db][4 * g + e] * inv; o[db][4 * g + e] = a; ss += a * a; }
.LBB0_450:
	v_mov_b32_e32 v2, v151
	s_and_b64 vcc, exec, s[58:59]
	v_lshrrev_b32_e32 v3, 6, v2
	v_and_b32_e32 v2, 63, v2
	v_lshlrev_b32_e32 v3, 14, v3
	v_lshl_or_b32 v246, v2, 4, v3
	v_add_u32_e32 v247, 0x1000, v246
	v_add_u32_e32 v248, 0x2000, v246
	v_add_u32_e32 v249, 0x3000, v246
	s_cbranch_vccz .LBB0_452
	global_load_dwordx4 v[4:7], v246, s[20:21] offset:0
	global_load_dwordx4 v[8:11], v246, s[20:21] offset:1024
	global_load_dwordx4 v[12:15], v246, s[20:21] offset:2048
	global_load_dwordx4 v[80:83], v246, s[20:21] offset:3072
	global_load_dwordx4 v[84:87], v247, s[20:21] offset:0
	global_load_dwordx4 v[88:91], v247, s[20:21] offset:1024
	global_load_dwordx4 v[92:95], v247, s[20:21] offset:2048
	global_load_dwordx4 v[98:101], v247, s[20:21] offset:3072
	global_load_dwordx4 v[102:105], v248, s[20:21] offset:0
	global_load_dwordx4 v[132:135], v248, s[20:21] offset:1024
	global_load_dwordx4 v[136:139], v248, s[20:21] offset:2048
	global_load_dwordx4 v[140:143], v248, s[20:21] offset:3072
	global_load_dwordx4 v[144:147], v249, s[20:21] offset:3072
	global_load_dwordx4 v[160:163], v249, s[20:21] offset:2048
	global_load_dwordx4 v[164:167], v249, s[20:21] offset:1024
	global_load_dwordx4 v[168:171], v249, s[20:21] offset:0
	v_mov_b32_e32 v96, v0
	v_mov_b32_e32 v97, v0
	s_nop 1
	v_permlane32_swap_b32_e32 v96, v97
	v_add_f32_e32 v96, v96, v97
	v_div_scale_f32 v97, s[10:11], v96, v96, v211
	v_rcp_f32_e32 v106, v97
	v_div_scale_f32 v107, vcc, v211, v96, v211
	v_fma_f32 v108, -v97, v106, 1.0
	v_fmac_f32_e32 v106, v108, v106
	v_mul_f32_e32 v108, v107, v106
	v_fma_f32 v109, -v97, v108, v107
	v_fmac_f32_e32 v108, v109, v106
	v_fma_f32 v97, -v97, v108, v107
	v_div_fmas_f32 v97, v97, v106, v108
	v_div_fixup_f32 v172, v97, v96, v211
	s_waitcnt vmcnt(15)
	v_pk_fma_f32 v[130:131], v[64:65], v[172:173], v[4:5] op_sel_hi:[1,0,1] neg_lo:[1,0,0] neg_hi:[1,0,0]
	v_pk_fma_f32 v[128:129], v[66:67], v[172:173], v[6:7] op_sel_hi:[1,0,1] neg_lo:[1,0,0] neg_hi:[1,0,0]
	s_waitcnt vmcnt(14)
	v_pk_fma_f32 v[126:127], v[68:69], v[172:173], v[8:9] op_sel_hi:[1,0,1] neg_lo:[1,0,0] neg_hi:[1,0,0]
	s_waitcnt vmcnt(12)
	v_pk_fma_f32 v[116:117], v[76:77], v[172:173], v[80:81] op_sel_hi:[1,0,1] neg_lo:[1,0,0] neg_hi:[1,0,0]
	v_pk_mul_f32 v[80:81], v[130:131], v[130:131]
	v_pk_fma_f32 v[114:115], v[78:79], v[172:173], v[82:83] op_sel_hi:[1,0,1] neg_lo:[1,0,0] neg_hi:[1,0,0]
	v_add_f32_e32 v80, v222, v80
	v_pk_mul_f32 v[82:83], v[128:129], v[128:129]
	v_add_f32_e32 v80, v81, v80
	v_add_f32_e32 v80, v82, v80
	s_waitcnt vmcnt(11)
	v_pk_fma_f32 v[118:119], v[48:49], v[172:173], v[84:85] op_sel_hi:[1,0,1] neg_lo:[1,0,0] neg_hi:[1,0,0]
	v_pk_mul_f32 v[84:85], v[126:127], v[126:127]
	v_add_f32_e32 v80, v83, v80
	v_pk_fma_f32 v[124:125], v[70:71], v[172:173], v[10:11] op_sel_hi:[1,0,1] neg_lo:[1,0,0] neg_hi:[1,0,0]
	v_add_f32_e32 v80, v84, v80
	s_waitcnt vmcnt(10)
	v_pk_fma_f32 v[110:111], v[52:53], v[172:173], v[88:89] op_sel_hi:[1,0,1] neg_lo:[1,0,0] neg_hi:[1,0,0]
	v_pk_mul_f32 v[88:89], v[124:125], v[124:125]
	v_add_f32_e32 v80, v85, v80
	v_pk_fma_f32 v[122:123], v[72:73], v[172:173], v[12:13] op_sel_hi:[1,0,1] neg_lo:[1,0,0] neg_hi:[1,0,0]
	v_add_f32_e32 v80, v88, v80
	s_waitcnt vmcnt(9)
	v_pk_fma_f32 v[106:107], v[56:57], v[172:173], v[92:93] op_sel_hi:[1,0,1] neg_lo:[1,0,0] neg_hi:[1,0,0]
	s_waitcnt vmcnt(8)
	v_pk_fma_f32 v[92:93], v[60:61], v[172:173], v[98:99] op_sel_hi:[1,0,1] neg_lo:[1,0,0] neg_hi:[1,0,0]
	v_pk_mul_f32 v[98:99], v[122:123], v[122:123]
	v_add_f32_e32 v80, v89, v80
	v_pk_fma_f32 v[120:121], v[74:75], v[172:173], v[14:15] op_sel_hi:[1,0,1] neg_lo:[1,0,0] neg_hi:[1,0,0]
	v_add_f32_e32 v80, v98, v80
	v_pk_fma_f32 v[108:109], v[54:55], v[172:173], v[90:91] op_sel_hi:[1,0,1] neg_lo:[1,0,0] neg_hi:[1,0,0]
	v_pk_fma_f32 v[90:91], v[62:63], v[172:173], v[100:101] op_sel_hi:[1,0,1] neg_lo:[1,0,0] neg_hi:[1,0,0]
	v_pk_mul_f32 v[100:101], v[120:121], v[120:121]
	v_add_f32_e32 v80, v99, v80
	v_add_f32_e32 v80, v100, v80
	v_pk_fma_f32 v[96:97], v[58:59], v[172:173], v[94:95] op_sel_hi:[1,0,1] neg_lo:[1,0,0] neg_hi:[1,0,0]
	s_waitcnt vmcnt(7)
	v_pk_fma_f32 v[94:95], v[32:33], v[172:173], v[102:103] op_sel_hi:[1,0,1] neg_lo:[1,0,0] neg_hi:[1,0,0]
	v_pk_mul_f32 v[102:103], v[116:117], v[116:117]
	v_add_f32_e32 v80, v101, v80
	v_add_f32_e32 v80, v102, v80
	v_pk_fma_f32 v[112:113], v[50:51], v[172:173], v[86:87] op_sel_hi:[1,0,1] neg_lo:[1,0,0] neg_hi:[1,0,0]
	v_pk_fma_f32 v[86:87], v[34:35], v[172:173], v[104:105] op_sel_hi:[1,0,1] neg_lo:[1,0,0] neg_hi:[1,0,0]
	v_pk_mul_f32 v[104:105], v[114:115], v[114:115]
	v_add_f32_e32 v80, v103, v80
	v_add_f32_e32 v80, v104, v80
	s_waitcnt vmcnt(6)
; __device__ __forceinline__ void da_unit(LAS unsigned char* lds, const AttnP& P, int seqbase, int S, int h, int qb, float lam) {
;     ...
;                 for (int g = 0; g < 4; ++g) {
;                     const f32x4 st = stash[db * 4 + g];
; #pragma unroll
;                     for (int e = 0; e < 4; ++e) { const float a = st[e] - o[db][4 * g + e] * inv; o[db][4 * g + e] = a; ss += a * a; }
	v_pk_fma_f32 v[14:15], v[36:37], v[172:173], v[132:133] op_sel_hi:[1,0,1] neg_lo:[1,0,0] neg_hi:[1,0,0]
	v_pk_mul_f32 v[132:133], v[118:119], v[118:119]
	v_add_f32_e32 v80, v105, v80
	v_add_f32_e32 v80, v132, v80
	v_pk_fma_f32 v[12:13], v[38:39], v[172:173], v[134:135] op_sel_hi:[1,0,1] neg_lo:[1,0,0] neg_hi:[1,0,0]
	v_pk_mul_f32 v[134:135], v[112:113], v[112:113]
	v_add_f32_e32 v80, v133, v80
	v_add_f32_e32 v80, v134, v80
	s_waitcnt vmcnt(5)
	v_pk_fma_f32 v[10:11], v[40:41], v[172:173], v[136:137] op_sel_hi:[1,0,1] neg_lo:[1,0,0] neg_hi:[1,0,0]
	v_pk_mul_f32 v[136:137], v[110:111], v[110:111]
	v_add_f32_e32 v80, v135, v80
	v_add_f32_e32 v80, v136, v80
	v_pk_fma_f32 v[8:9], v[42:43], v[172:173], v[138:139] op_sel_hi:[1,0,1] neg_lo:[1,0,0] neg_hi:[1,0,0]
	v_pk_mul_f32 v[138:139], v[108:109], v[108:109]
	v_add_f32_e32 v80, v137, v80
	v_add_f32_e32 v80, v138, v80
	s_waitcnt vmcnt(4)
	v_pk_fma_f32 v[6:7], v[44:45], v[172:173], v[140:141] op_sel_hi:[1,0,1] neg_lo:[1,0,0] neg_hi:[1,0,0]
	v_pk_mul_f32 v[140:141], v[106:107], v[106:107]
	v_add_f32_e32 v80, v139, v80
	v_add_f32_e32 v80, v140, v80
	v_pk_fma_f32 v[4:5], v[46:47], v[172:173], v[142:143] op_sel_hi:[1,0,1] neg_lo:[1,0,0] neg_hi:[1,0,0]
	v_pk_mul_f32 v[142:143], v[96:97], v[96:97]
	v_add_f32_e32 v80, v141, v80
	v_add_f32_e32 v80, v142, v80
	v_pk_mul_f32 v[174:175], v[92:93], v[92:93]
	v_add_f32_e32 v80, v143, v80
	v_add_f32_e32 v80, v174, v80
	v_pk_mul_f32 v[176:177], v[90:91], v[90:91]
	v_add_f32_e32 v80, v175, v80
	v_add_f32_e32 v80, v176, v80
	v_pk_mul_f32 v[178:179], v[94:95], v[94:95]
	v_add_f32_e32 v80, v177, v80
	v_add_f32_e32 v80, v178, v80
	v_pk_mul_f32 v[180:181], v[86:87], v[86:87]
	v_add_f32_e32 v80, v179, v80
	v_add_f32_e32 v80, v180, v80
	v_pk_mul_f32 v[182:183], v[14:15], v[14:15]
	v_add_f32_e32 v80, v181, v80
	v_add_f32_e32 v80, v182, v80
	v_pk_mul_f32 v[184:185], v[12:13], v[12:13]
	v_add_f32_e32 v80, v183, v80
	v_add_f32_e32 v80, v184, v80
	v_pk_mul_f32 v[186:187], v[10:11], v[10:11]
	v_add_f32_e32 v80, v185, v80
	v_add_f32_e32 v80, v186, v80
	v_pk_mul_f32 v[188:189], v[8:9], v[8:9]
	v_add_f32_e32 v80, v187, v80
	v_add_f32_e32 v80, v188, v80
	v_pk_mul_f32 v[190:191], v[6:7], v[6:7]
	v_add_f32_e32 v80, v189, v80
	v_add_f32_e32 v80, v190, v80
	v_add_f32_e32 v82, v191, v80
	v_pk_mul_f32 v[80:81], v[4:5], v[4:5]
	s_waitcnt vmcnt(0)
	v_pk_fma_f32 v[102:103], v[16:17], v[172:173], v[168:169] op_sel_hi:[1,0,1] neg_lo:[1,0,0] neg_hi:[1,0,0]
	v_add_f32_e32 v80, v80, v82
	v_add_f32_e32 v82, v81, v80
	v_pk_mul_f32 v[80:81], v[102:103], v[102:103]
	v_pk_fma_f32 v[104:105], v[18:19], v[172:173], v[170:171] op_sel_hi:[1,0,1] neg_lo:[1,0,0] neg_hi:[1,0,0]
	v_add_f32_e32 v80, v80, v82
	v_add_f32_e32 v82, v81, v80
	v_pk_mul_f32 v[80:81], v[104:105], v[104:105]
	v_pk_fma_f32 v[98:99], v[20:21], v[172:173], v[164:165] op_sel_hi:[1,0,1] neg_lo:[1,0,0] neg_hi:[1,0,0]
	v_add_f32_e32 v80, v80, v82
	v_add_f32_e32 v82, v81, v80
	v_pk_mul_f32 v[80:81], v[98:99], v[98:99]
	v_pk_fma_f32 v[100:101], v[22:23], v[172:173], v[166:167] op_sel_hi:[1,0,1] neg_lo:[1,0,0] neg_hi:[1,0,0]
	v_add_f32_e32 v80, v80, v82
	v_add_f32_e32 v82, v81, v80
	v_pk_mul_f32 v[80:81], v[100:101], v[100:101]
	v_pk_fma_f32 v[88:89], v[24:25], v[172:173], v[160:161] op_sel_hi:[1,0,1] neg_lo:[1,0,0] neg_hi:[1,0,0]
	v_add_f32_e32 v80, v80, v82
	v_add_f32_e32 v82, v81, v80
	v_pk_mul_f32 v[80:81], v[88:89], v[88:89]
	v_pk_fma_f32 v[84:85], v[26:27], v[172:173], v[162:163] op_sel_hi:[1,0,1] neg_lo:[1,0,0] neg_hi:[1,0,0]
	v_add_f32_e32 v80, v80, v82
	v_add_f32_e32 v82, v81, v80
	v_pk_mul_f32 v[80:81], v[84:85], v[84:85]
	s_nop 0
	v_add_f32_e32 v80, v80, v82
	v_add_f32_e32 v132, v81, v80
	v_pk_fma_f32 v[80:81], v[28:29], v[172:173], v[144:145] op_sel_hi:[1,0,1] neg_lo:[1,0,0] neg_hi:[1,0,0]
	s_nop 0
	v_pk_mul_f32 v[82:83], v[80:81], v[80:81]
	s_nop 0
	v_add_f32_e32 v82, v82, v132
	v_add_f32_e32 v134, v83, v82
	v_pk_fma_f32 v[82:83], v[30:31], v[172:173], v[146:147] op_sel_hi:[1,0,1] neg_lo:[1,0,0] neg_hi:[1,0,0]
	s_nop 0
	v_pk_mul_f32 v[132:133], v[82:83], v[82:83]
	s_nop 0
	v_add_f32_e32 v132, v132, v134
	v_add_f32_e32 v132, v133, v132
	s_cbranch_execz .LBB0_453
	s_branch .LBB0_454

; __device__ __forceinline__ float hsum(float v) { auto rr = __builtin_amdgcn_permlane32_swap(__float_as_uint(v), __float_as_uint(v), false, false); return __uint_as_float(rr[0]) + __uint_as_float(rr[1]); }
; __device__ __forceinline__ void da_unit(LAS unsigned char* lds, const AttnP& P, int seqbase, int S, int h, int qb, float lam) {
;     ...
;         if (map == 0) {
;             const float inv = 1.0f / hsum(l);
; #pragma unroll
;             for (int db = 0; db < 4; ++db)
; #pragma unroll
;                 for (int g = 0; g < 4; ++g) stash[db * 4 + g] = (f32x4){o[db][4 * g], o[db][4 * g + 1], o[db][4 * g + 2], o[db][4 * g + 3]} * inv;
.LBB0_453:
	v_mov_b32_e32 v132, v0
	s_nop 1
	v_permlane32_swap_b32_e32 v0, v132
	v_add_f32_e32 v0, v0, v132
	v_div_scale_f32 v132, s[10:11], v0, v0, 1.0
	v_rcp_f32_e32 v133, v132
	s_nop 0
	v_fma_f32 v134, -v132, v133, 1.0
	v_fmac_f32_e32 v133, v134, v133
	v_div_scale_f32 v134, vcc, 1.0, v0, 1.0
	v_mul_f32_e32 v135, v134, v133
	v_fma_f32 v136, -v132, v135, v134
	v_fmac_f32_e32 v135, v136, v133
	v_fma_f32 v132, -v132, v135, v134
	v_div_fmas_f32 v132, v132, v133, v135
	v_div_fixup_f32 v0, v132, v0, 1.0
	v_pk_mul_f32 v[66:67], v[66:67], v[0:1] op_sel_hi:[1,0]
	v_pk_mul_f32 v[64:65], v[64:65], v[0:1] op_sel_hi:[1,0]
	v_pk_mul_f32 v[50:51], v[50:51], v[0:1] op_sel_hi:[1,0]
	v_pk_mul_f32 v[48:49], v[48:49], v[0:1] op_sel_hi:[1,0]
	v_pk_mul_f32 v[34:35], v[34:35], v[0:1] op_sel_hi:[1,0]
	v_pk_mul_f32 v[32:33], v[32:33], v[0:1] op_sel_hi:[1,0]
	v_pk_mul_f32 v[18:19], v[18:19], v[0:1] op_sel_hi:[1,0]
	v_pk_mul_f32 v[16:17], v[16:17], v[0:1] op_sel_hi:[1,0]
	global_store_dwordx4 v246, v[64:67], s[20:21] offset:0
	global_store_dwordx4 v247, v[48:51], s[20:21] offset:0
	global_store_dwordx4 v248, v[32:35], s[20:21] offset:0
	v_pk_mul_f32 v[66:67], v[70:71], v[0:1] op_sel_hi:[1,0]
	v_pk_mul_f32 v[64:65], v[68:69], v[0:1] op_sel_hi:[1,0]
	v_pk_mul_f32 v[50:51], v[54:55], v[0:1] op_sel_hi:[1,0]
	v_pk_mul_f32 v[48:49], v[52:53], v[0:1] op_sel_hi:[1,0]
	v_pk_mul_f32 v[34:35], v[38:39], v[0:1] op_sel_hi:[1,0]
	v_pk_mul_f32 v[32:33], v[36:37], v[0:1] op_sel_hi:[1,0]
	global_store_dwordx4 v249, v[16:19], s[20:21] offset:0
	global_store_dwordx4 v246, v[64:67], s[20:21] offset:1024
	global_store_dwordx4 v247, v[48:51], s[20:21] offset:1024
	v_pk_mul_f32 v[18:19], v[22:23], v[0:1] op_sel_hi:[1,0]
	v_pk_mul_f32 v[16:17], v[20:21], v[0:1] op_sel_hi:[1,0]
	v_pk_mul_f32 v[66:67], v[74:75], v[0:1] op_sel_hi:[1,0]
	v_pk_mul_f32 v[64:65], v[72:73], v[0:1] op_sel_hi:[1,0]
	v_pk_mul_f32 v[50:51], v[58:59], v[0:1] op_sel_hi:[1,0]
	v_pk_mul_f32 v[48:49], v[56:57], v[0:1] op_sel_hi:[1,0]
	global_store_dwordx4 v248, v[32:35], s[20:21] offset:1024
	global_store_dwordx4 v249, v[16:19], s[20:21] offset:1024
	global_store_dwordx4 v246, v[64:67], s[20:21] offset:2048
	v_pk_mul_f32 v[34:35], v[42:43], v[0:1] op_sel_hi:[1,0]
	v_pk_mul_f32 v[32:33], v[40:41], v[0:1] op_sel_hi:[1,0]
	v_pk_mul_f32 v[18:19], v[26:27], v[0:1] op_sel_hi:[1,0]
	v_pk_mul_f32 v[16:17], v[24:25], v[0:1] op_sel_hi:[1,0]
	v_pk_mul_f32 v[66:67], v[78:79], v[0:1] op_sel_hi:[1,0]
	v_pk_mul_f32 v[64:65], v[76:77], v[0:1] op_sel_hi:[1,0]
	global_store_dwordx4 v247, v[48:51], s[20:21] offset:2048
	global_store_dwordx4 v248, v[32:35], s[20:21] offset:2048
	global_store_dwordx4 v249, v[16:19], s[20:21] offset:2048
	v_pk_mul_f32 v[50:51], v[62:63], v[0:1] op_sel_hi:[1,0]
	v_pk_mul_f32 v[48:49], v[60:61], v[0:1] op_sel_hi:[1,0]
	v_pk_mul_f32 v[34:35], v[46:47], v[0:1] op_sel_hi:[1,0]
	v_pk_mul_f32 v[32:33], v[44:45], v[0:1] op_sel_hi:[1,0]
	v_pk_mul_f32 v[18:19], v[30:31], v[0:1] op_sel_hi:[1,0]
	v_pk_mul_f32 v[16:17], v[28:29], v[0:1] op_sel_hi:[1,0]
	v_mov_b32_e32 v132, v222
	global_store_dwordx4 v246, v[64:67], s[20:21] offset:3072
	global_store_dwordx4 v247, v[48:51], s[20:21] offset:3072
	global_store_dwordx4 v248, v[32:35], s[20:21] offset:3072
	global_store_dwordx4 v249, v[16:19], s[20:21] offset:3072
